# stack with SwiGLU epilogue non-transcendental ops as v_pk_mul/add_f32 (bit-exact per lane)
# baseline (speedup 1.0000x reference)
.LBB0_170:
	v_lshl_or_b32 v150, s34, 7, v146
	v_lshl_add_u32 v148, s36, 8, v144
	v_ashrrev_i32_e32 v151, 31, v150
	v_mov_b64_e32 v[142:143], s[20:21]
	s_andn2_b64 vcc, exec, s[4:5]
	s_movk_i32 s65, 0xff5d
	s_movk_i32 s64, 0xff7c
	v_lshlrev_b64 v[152:153], 1, v[150:151]
	v_mov_b32_e32 v194, 0xbfb8aa3b
	v_mov_b32_e32 v195, 0xbfb8aa3b
	v_add_u32_e32 v192, 0, v148
	v_pk_mul_f32 v[156:157], v[126:127], v[194:195]
	v_pk_mul_f32 v[158:159], v[128:129], v[194:195]
	v_pk_mul_f32 v[160:161], v[118:119], v[194:195]
	v_pk_mul_f32 v[162:163], v[120:121], v[194:195]
	v_mad_i64_i32 v[188:189], s[34:35], v192, s47, v[142:143]
	v_exp_f32_e32 v156, v156
	v_exp_f32_e32 v157, v157
	v_exp_f32_e32 v158, v158
	v_exp_f32_e32 v159, v159
	v_exp_f32_e32 v160, v160
	v_exp_f32_e32 v161, v161
	v_exp_f32_e32 v162, v162
	v_exp_f32_e32 v163, v163
	v_lshl_add_u64 v[188:189], v[188:189], 0, v[152:153]
	v_pk_add_f32 v[156:157], v[156:157], 1.0 op_sel_hi:[1,0]
	v_pk_add_f32 v[158:159], v[158:159], 1.0 op_sel_hi:[1,0]
	v_pk_add_f32 v[160:161], v[160:161], 1.0 op_sel_hi:[1,0]
	v_pk_add_f32 v[162:163], v[162:163], 1.0 op_sel_hi:[1,0]
	v_rcp_f32_e32 v156, v156
	v_rcp_f32_e32 v157, v157
	v_rcp_f32_e32 v158, v158
	v_rcp_f32_e32 v159, v159
	v_rcp_f32_e32 v160, v160
	v_rcp_f32_e32 v161, v161
	v_rcp_f32_e32 v162, v162
	v_rcp_f32_e32 v163, v163
	v_pk_mul_f32 v[156:157], v[126:127], v[156:157]
	v_pk_mul_f32 v[158:159], v[128:129], v[158:159]
	v_pk_mul_f32 v[160:161], v[118:119], v[160:161]
	v_pk_mul_f32 v[162:163], v[120:121], v[162:163]
	v_pk_mul_f32 v[156:157], v[156:157], v[122:123]
	v_pk_mul_f32 v[158:159], v[158:159], v[124:125]
	v_pk_mul_f32 v[160:161], v[160:161], v[114:115]
	v_pk_mul_f32 v[162:163], v[162:163], v[116:117]
	v_cvt_pk_bf16_f32 v180, v156, v157
	v_cvt_pk_bf16_f32 v181, v158, v159
	v_cvt_pk_bf16_f32 v182, v160, v161
	v_cvt_pk_bf16_f32 v183, v162, v163
	global_store_dwordx4 v[188:189], v[180:183], off
	v_add_u32_e32 v193, 16, v148
	v_pk_mul_f32 v[164:165], v[110:111], v[194:195]
	v_pk_mul_f32 v[166:167], v[112:113], v[194:195]
	v_pk_mul_f32 v[168:169], v[102:103], v[194:195]
	v_pk_mul_f32 v[170:171], v[104:105], v[194:195]
	v_mad_i64_i32 v[190:191], s[34:35], v193, s47, v[142:143]
	v_exp_f32_e32 v164, v164
	v_exp_f32_e32 v165, v165
	v_exp_f32_e32 v166, v166
	v_exp_f32_e32 v167, v167
	v_exp_f32_e32 v168, v168
	v_exp_f32_e32 v169, v169
	v_exp_f32_e32 v170, v170
	v_exp_f32_e32 v171, v171
	v_lshl_add_u64 v[190:191], v[190:191], 0, v[152:153]
	v_pk_add_f32 v[164:165], v[164:165], 1.0 op_sel_hi:[1,0]
	v_pk_add_f32 v[166:167], v[166:167], 1.0 op_sel_hi:[1,0]
	v_pk_add_f32 v[168:169], v[168:169], 1.0 op_sel_hi:[1,0]
	v_pk_add_f32 v[170:171], v[170:171], 1.0 op_sel_hi:[1,0]
	v_rcp_f32_e32 v164, v164
	v_rcp_f32_e32 v165, v165
	v_rcp_f32_e32 v166, v166
	v_rcp_f32_e32 v167, v167
	v_rcp_f32_e32 v168, v168
	v_rcp_f32_e32 v169, v169
	v_rcp_f32_e32 v170, v170
	v_rcp_f32_e32 v171, v171
	v_pk_mul_f32 v[164:165], v[110:111], v[164:165]
	v_pk_mul_f32 v[166:167], v[112:113], v[166:167]
	v_pk_mul_f32 v[168:169], v[102:103], v[168:169]
	v_pk_mul_f32 v[170:171], v[104:105], v[170:171]
	v_pk_mul_f32 v[164:165], v[164:165], v[106:107]
	v_pk_mul_f32 v[166:167], v[166:167], v[108:109]
	v_pk_mul_f32 v[168:169], v[168:169], v[98:99]
	v_pk_mul_f32 v[170:171], v[170:171], v[100:101]
	v_cvt_pk_bf16_f32 v184, v164, v165
	v_cvt_pk_bf16_f32 v185, v166, v167
	v_cvt_pk_bf16_f32 v186, v168, v169
	v_cvt_pk_bf16_f32 v187, v170, v171
	global_store_dwordx4 v[190:191], v[184:187], off
	v_add_u32_e32 v192, 32, v148
	v_pk_mul_f32 v[156:157], v[94:95], v[194:195]
	v_pk_mul_f32 v[158:159], v[96:97], v[194:195]
	v_pk_mul_f32 v[160:161], v[86:87], v[194:195]
	v_pk_mul_f32 v[162:163], v[88:89], v[194:195]
	v_mad_i64_i32 v[188:189], s[34:35], v192, s47, v[142:143]
	v_exp_f32_e32 v156, v156
	v_exp_f32_e32 v157, v157
	v_exp_f32_e32 v158, v158
	v_exp_f32_e32 v159, v159
	v_exp_f32_e32 v160, v160
	v_exp_f32_e32 v161, v161
	v_exp_f32_e32 v162, v162
	v_exp_f32_e32 v163, v163
	v_lshl_add_u64 v[188:189], v[188:189], 0, v[152:153]
	v_pk_add_f32 v[156:157], v[156:157], 1.0 op_sel_hi:[1,0]
	v_pk_add_f32 v[158:159], v[158:159], 1.0 op_sel_hi:[1,0]
	v_pk_add_f32 v[160:161], v[160:161], 1.0 op_sel_hi:[1,0]
	v_pk_add_f32 v[162:163], v[162:163], 1.0 op_sel_hi:[1,0]
	v_rcp_f32_e32 v156, v156
	v_rcp_f32_e32 v157, v157
	v_rcp_f32_e32 v158, v158
	v_rcp_f32_e32 v159, v159
	v_rcp_f32_e32 v160, v160
	v_rcp_f32_e32 v161, v161
	v_rcp_f32_e32 v162, v162
	v_rcp_f32_e32 v163, v163
	v_pk_mul_f32 v[156:157], v[94:95], v[156:157]
	v_pk_mul_f32 v[158:159], v[96:97], v[158:159]
	v_pk_mul_f32 v[160:161], v[86:87], v[160:161]
	v_pk_mul_f32 v[162:163], v[88:89], v[162:163]
	v_pk_mul_f32 v[156:157], v[156:157], v[90:91]
	v_pk_mul_f32 v[158:159], v[158:159], v[92:93]
	v_pk_mul_f32 v[160:161], v[160:161], v[82:83]
	v_pk_mul_f32 v[162:163], v[162:163], v[84:85]
	v_cvt_pk_bf16_f32 v180, v156, v157
	v_cvt_pk_bf16_f32 v181, v158, v159
	v_cvt_pk_bf16_f32 v182, v160, v161
	v_cvt_pk_bf16_f32 v183, v162, v163
	global_store_dwordx4 v[188:189], v[180:183], off
	v_add_u32_e32 v193, 48, v148
	v_pk_mul_f32 v[164:165], v[78:79], v[194:195]
	v_pk_mul_f32 v[166:167], v[80:81], v[194:195]
	v_pk_mul_f32 v[168:169], v[70:71], v[194:195]
	v_pk_mul_f32 v[170:171], v[72:73], v[194:195]
	v_mad_i64_i32 v[190:191], s[34:35], v193, s47, v[142:143]
	v_exp_f32_e32 v164, v164
	v_exp_f32_e32 v165, v165
	v_exp_f32_e32 v166, v166
	v_exp_f32_e32 v167, v167
	v_exp_f32_e32 v168, v168
	v_exp_f32_e32 v169, v169
	v_exp_f32_e32 v170, v170
	v_exp_f32_e32 v171, v171
	v_lshl_add_u64 v[190:191], v[190:191], 0, v[152:153]
	v_pk_add_f32 v[164:165], v[164:165], 1.0 op_sel_hi:[1,0]
	v_pk_add_f32 v[166:167], v[166:167], 1.0 op_sel_hi:[1,0]
	v_pk_add_f32 v[168:169], v[168:169], 1.0 op_sel_hi:[1,0]
	v_pk_add_f32 v[170:171], v[170:171], 1.0 op_sel_hi:[1,0]
	v_rcp_f32_e32 v164, v164
	v_rcp_f32_e32 v165, v165
	v_rcp_f32_e32 v166, v166
	v_rcp_f32_e32 v167, v167
	v_rcp_f32_e32 v168, v168
	v_rcp_f32_e32 v169, v169
	v_rcp_f32_e32 v170, v170
	v_rcp_f32_e32 v171, v171
	v_pk_mul_f32 v[164:165], v[78:79], v[164:165]
	v_pk_mul_f32 v[166:167], v[80:81], v[166:167]
	v_pk_mul_f32 v[168:169], v[70:71], v[168:169]
	v_pk_mul_f32 v[170:171], v[72:73], v[170:171]
	v_pk_mul_f32 v[164:165], v[164:165], v[74:75]
	v_pk_mul_f32 v[166:167], v[166:167], v[76:77]
	v_pk_mul_f32 v[168:169], v[168:169], v[66:67]
	v_pk_mul_f32 v[170:171], v[170:171], v[68:69]
	v_cvt_pk_bf16_f32 v184, v164, v165
	v_cvt_pk_bf16_f32 v185, v166, v167
	v_cvt_pk_bf16_f32 v186, v168, v169
	v_cvt_pk_bf16_f32 v187, v170, v171
	global_store_dwordx4 v[190:191], v[184:187], off
	v_add_u32_e32 v192, 0x80, v148
	v_pk_mul_f32 v[156:157], v[62:63], v[194:195]
	v_pk_mul_f32 v[158:159], v[64:65], v[194:195]
	v_pk_mul_f32 v[160:161], v[54:55], v[194:195]
	v_pk_mul_f32 v[162:163], v[56:57], v[194:195]
	v_mad_i64_i32 v[188:189], s[34:35], v192, s47, v[142:143]
	v_exp_f32_e32 v156, v156
	v_exp_f32_e32 v157, v157
	v_exp_f32_e32 v158, v158
	v_exp_f32_e32 v159, v159
	v_exp_f32_e32 v160, v160
	v_exp_f32_e32 v161, v161
	v_exp_f32_e32 v162, v162
	v_exp_f32_e32 v163, v163
	v_lshl_add_u64 v[188:189], v[188:189], 0, v[152:153]
	v_pk_add_f32 v[156:157], v[156:157], 1.0 op_sel_hi:[1,0]
	v_pk_add_f32 v[158:159], v[158:159], 1.0 op_sel_hi:[1,0]
	v_pk_add_f32 v[160:161], v[160:161], 1.0 op_sel_hi:[1,0]
	v_pk_add_f32 v[162:163], v[162:163], 1.0 op_sel_hi:[1,0]
	v_rcp_f32_e32 v156, v156
	v_rcp_f32_e32 v157, v157
	v_rcp_f32_e32 v158, v158
	v_rcp_f32_e32 v159, v159
	v_rcp_f32_e32 v160, v160
	v_rcp_f32_e32 v161, v161
	v_rcp_f32_e32 v162, v162
	v_rcp_f32_e32 v163, v163
	v_pk_mul_f32 v[156:157], v[62:63], v[156:157]
	v_pk_mul_f32 v[158:159], v[64:65], v[158:159]
	v_pk_mul_f32 v[160:161], v[54:55], v[160:161]
	v_pk_mul_f32 v[162:163], v[56:57], v[162:163]
	v_pk_mul_f32 v[156:157], v[156:157], v[58:59]
	v_pk_mul_f32 v[158:159], v[158:159], v[60:61]
	v_pk_mul_f32 v[160:161], v[160:161], v[50:51]
	v_pk_mul_f32 v[162:163], v[162:163], v[52:53]
	v_cvt_pk_bf16_f32 v180, v156, v157
	v_cvt_pk_bf16_f32 v181, v158, v159
	v_cvt_pk_bf16_f32 v182, v160, v161
	v_cvt_pk_bf16_f32 v183, v162, v163
	global_store_dwordx4 v[188:189], v[180:183], off
	v_add_u32_e32 v193, 0x90, v148
	v_pk_mul_f32 v[164:165], v[46:47], v[194:195]
	v_pk_mul_f32 v[166:167], v[48:49], v[194:195]
	v_pk_mul_f32 v[168:169], v[38:39], v[194:195]
	v_pk_mul_f32 v[170:171], v[40:41], v[194:195]
	v_mad_i64_i32 v[190:191], s[34:35], v193, s47, v[142:143]
	v_exp_f32_e32 v164, v164
	v_exp_f32_e32 v165, v165
	v_exp_f32_e32 v166, v166
	v_exp_f32_e32 v167, v167
	v_exp_f32_e32 v168, v168
	v_exp_f32_e32 v169, v169
	v_exp_f32_e32 v170, v170
	v_exp_f32_e32 v171, v171
	v_lshl_add_u64 v[190:191], v[190:191], 0, v[152:153]
	v_pk_add_f32 v[164:165], v[164:165], 1.0 op_sel_hi:[1,0]
	v_pk_add_f32 v[166:167], v[166:167], 1.0 op_sel_hi:[1,0]
	v_pk_add_f32 v[168:169], v[168:169], 1.0 op_sel_hi:[1,0]
	v_pk_add_f32 v[170:171], v[170:171], 1.0 op_sel_hi:[1,0]
	v_rcp_f32_e32 v164, v164
	v_rcp_f32_e32 v165, v165
	v_rcp_f32_e32 v166, v166
	v_rcp_f32_e32 v167, v167
	v_rcp_f32_e32 v168, v168
	v_rcp_f32_e32 v169, v169
	v_rcp_f32_e32 v170, v170
	v_rcp_f32_e32 v171, v171
	v_pk_mul_f32 v[164:165], v[46:47], v[164:165]
	v_pk_mul_f32 v[166:167], v[48:49], v[166:167]
	v_pk_mul_f32 v[168:169], v[38:39], v[168:169]
	v_pk_mul_f32 v[170:171], v[40:41], v[170:171]
	v_pk_mul_f32 v[164:165], v[164:165], v[42:43]
	v_pk_mul_f32 v[166:167], v[166:167], v[44:45]
	v_pk_mul_f32 v[168:169], v[168:169], v[34:35]
	v_pk_mul_f32 v[170:171], v[170:171], v[36:37]
	v_cvt_pk_bf16_f32 v184, v164, v165
	v_cvt_pk_bf16_f32 v185, v166, v167
	v_cvt_pk_bf16_f32 v186, v168, v169
	v_cvt_pk_bf16_f32 v187, v170, v171
	global_store_dwordx4 v[190:191], v[184:187], off
	v_add_u32_e32 v192, 0xa0, v148
	v_pk_mul_f32 v[156:157], v[30:31], v[194:195]
	v_pk_mul_f32 v[158:159], v[32:33], v[194:195]
	v_pk_mul_f32 v[160:161], v[22:23], v[194:195]
	v_pk_mul_f32 v[162:163], v[24:25], v[194:195]
	v_mad_i64_i32 v[188:189], s[34:35], v192, s47, v[142:143]
	v_exp_f32_e32 v156, v156
	v_exp_f32_e32 v157, v157
	v_exp_f32_e32 v158, v158
	v_exp_f32_e32 v159, v159
	v_exp_f32_e32 v160, v160
	v_exp_f32_e32 v161, v161
	v_exp_f32_e32 v162, v162
	v_exp_f32_e32 v163, v163
	v_lshl_add_u64 v[188:189], v[188:189], 0, v[152:153]
	v_pk_add_f32 v[156:157], v[156:157], 1.0 op_sel_hi:[1,0]
	v_pk_add_f32 v[158:159], v[158:159], 1.0 op_sel_hi:[1,0]
	v_pk_add_f32 v[160:161], v[160:161], 1.0 op_sel_hi:[1,0]
	v_pk_add_f32 v[162:163], v[162:163], 1.0 op_sel_hi:[1,0]
	v_rcp_f32_e32 v156, v156
	v_rcp_f32_e32 v157, v157
	v_rcp_f32_e32 v158, v158
	v_rcp_f32_e32 v159, v159
	v_rcp_f32_e32 v160, v160
	v_rcp_f32_e32 v161, v161
	v_rcp_f32_e32 v162, v162
	v_rcp_f32_e32 v163, v163
	v_pk_mul_f32 v[156:157], v[30:31], v[156:157]
	v_pk_mul_f32 v[158:159], v[32:33], v[158:159]
	v_pk_mul_f32 v[160:161], v[22:23], v[160:161]
	v_pk_mul_f32 v[162:163], v[24:25], v[162:163]
	v_pk_mul_f32 v[156:157], v[156:157], v[26:27]
	v_pk_mul_f32 v[158:159], v[158:159], v[28:29]
	v_pk_mul_f32 v[160:161], v[160:161], v[18:19]
	v_pk_mul_f32 v[162:163], v[162:163], v[20:21]
	v_cvt_pk_bf16_f32 v180, v156, v157
	v_cvt_pk_bf16_f32 v181, v158, v159
	v_cvt_pk_bf16_f32 v182, v160, v161
	v_cvt_pk_bf16_f32 v183, v162, v163
	global_store_dwordx4 v[188:189], v[180:183], off
	v_add_u32_e32 v193, 0xb0, v148
	v_pk_mul_f32 v[164:165], v[14:15], v[194:195]
	v_pk_mul_f32 v[166:167], v[16:17], v[194:195]
	v_pk_mul_f32 v[168:169], v[6:7], v[194:195]
	v_pk_mul_f32 v[170:171], v[8:9], v[194:195]
	v_mad_i64_i32 v[190:191], s[34:35], v193, s47, v[142:143]
	v_exp_f32_e32 v164, v164
	v_exp_f32_e32 v165, v165
	v_exp_f32_e32 v166, v166
	v_exp_f32_e32 v167, v167
	v_exp_f32_e32 v168, v168
	v_exp_f32_e32 v169, v169
	v_exp_f32_e32 v170, v170
	v_exp_f32_e32 v171, v171
	v_lshl_add_u64 v[190:191], v[190:191], 0, v[152:153]
	v_pk_add_f32 v[164:165], v[164:165], 1.0 op_sel_hi:[1,0]
	v_pk_add_f32 v[166:167], v[166:167], 1.0 op_sel_hi:[1,0]
	v_pk_add_f32 v[168:169], v[168:169], 1.0 op_sel_hi:[1,0]
	v_pk_add_f32 v[170:171], v[170:171], 1.0 op_sel_hi:[1,0]
	v_rcp_f32_e32 v164, v164
	v_rcp_f32_e32 v165, v165
	v_rcp_f32_e32 v166, v166
	v_rcp_f32_e32 v167, v167
	v_rcp_f32_e32 v168, v168
	v_rcp_f32_e32 v169, v169
	v_rcp_f32_e32 v170, v170
	v_rcp_f32_e32 v171, v171
	v_pk_mul_f32 v[164:165], v[14:15], v[164:165]
	v_pk_mul_f32 v[166:167], v[16:17], v[166:167]
	v_pk_mul_f32 v[168:169], v[6:7], v[168:169]
	v_pk_mul_f32 v[170:171], v[8:9], v[170:171]
	v_pk_mul_f32 v[164:165], v[164:165], v[10:11]
	v_pk_mul_f32 v[166:167], v[166:167], v[12:13]
	v_pk_mul_f32 v[168:169], v[168:169], v[2:3]
	v_pk_mul_f32 v[170:171], v[170:171], v[4:5]
	v_cvt_pk_bf16_f32 v184, v164, v165
	v_cvt_pk_bf16_f32 v185, v166, v167
	v_cvt_pk_bf16_f32 v186, v168, v169
	v_cvt_pk_bf16_f32 v187, v170, v171
	global_store_dwordx4 v[190:191], v[184:187], off
	s_mov_b64 s[34:35], -1
	s_cbranch_vccnz .LBB0_163
	s_andn2_b64 vcc, exec, s[12:13]
	s_cbranch_vccnz .LBB0_162
	s_barrier
	s_branch .LBB0_162
